# E1/E2 tile setup: parallel expert search (one LDS read + popcount) instead of serial LDS loop; cnt[e] from LDS prefix
# speedup vs baseline: 1.0434x; 1.0230x over previous
; template <bool ABF, bool BBF, class RowF, class ColF, class Epi>
; __device__ __forceinline__ void gemm_tile(char* smem, int K, RowF rowptr, ColF colptr, int ldb, Epi epi) {
;     ...
;   auto gload = [&](int k0) {
; #pragma unroll
;     for (int i = 0; i < NA; i++) ra[i] = *(const u32x4*)(ap[i] + (size_t)k0 * (ABF ? 2 : 4));
;     if (BBF) {
; #pragma unroll
;       for (int i = 0; i < 4; i++) rbb[BBF ? i : 0] = *(const u32x4*)(bq[i] + (size_t)k0 * 2);
;     } else {
;       const float* b = bp + (size_t)k0 * ldb;
; #pragma unroll
;       for (int j = 0; j < 32; j++) rb[BBF ? 0 : j] = b[(size_t)j * ldb];
;     }
;   };
;   auto sstore = [&](int buf) {
;     u16* As = As0 + buf * (GEMM_SMEM / 2);
;     u16* Bs = As + BM * LDT;
; #pragma unroll
;     for (int i = 0; i < NA; i++) {
;       if (ABF) {
;         { const int row = ar0 + ARS * i; *(u32x4*)&As[row * LDT + (((ac >> 3) ^ ((row >> 1) & 7)) << 3)] = ra[i]; }
;       } else {
;         u32x2 v;
;         v[0] = pack2(__uint_as_float(ra[i][0]), __uint_as_float(ra[i][1]));
;         v[1] = pack2(__uint_as_float(ra[i][2]), __uint_as_float(ra[i][3]));
;         { const int row = ar0 + ARS * i; *(u32x2*)&As[row * LDT + (((ac >> 3) ^ ((row >> 1) & 7)) << 3) + (ac & 4)] = v; }
;       }
;     }
;     if (BBF) {
; #pragma unroll
;       for (int i = 0; i < 4; i++) { const int row = br0 + 32 * i; *(u32x4*)&Bs[row * LDT + (((bcc >> 3) ^ ((row >> 1) & 7)) << 3)] = rbb[BBF ? i : 0]; }
;     } else {
; #pragma unroll
;       for (int j = 0; j < 4; j++) {
;         u32x4 v;
; __device__ void phaseE1(const Params& p, char* smem) {
;     ...
;   xcd_queue_run(p.bar + QW_BASE + 1024, s_rb[NEXP], smem + 2 * GEMM_SMEM + 800, [&](int j, int q) {
;     const int rbg = q, jt = j;
;     int e = 0;
;     while (s_rb[e + 1] <= rbg) e++;
;     const int rb = rbg - s_rb[e];
;     const int cnt = p.cnt[e];
;     const int rows = min(128, cnt - rb * 128);
;     const int* lt = p.list_tok + e * CAP + rb * 128;
;     const int slot0 = s_off[e] + rb * 128;
;     const int j0 = jt * 64;
;     const u16* wg = p.WgT + (size_t)e * DEXP * DM;
;     const u16* wu = p.WuT + (size_t)e * DEXP * DM;
;     auto rowf = [&](int r) { int rr = r < rows ? r : 0; return (const void*)(p.X1B + (size_t)lt[rr] * DM); };
;     auto colf = [&](int c) { return (const void*)(((c & 32) ? wu : wg) + (size_t)(j0 + (c >> 6) * 32 + (c & 31)) * DM); };
.LBB0_1273:
	s_or_b64 exec, exec, s[16:17]
	s_cmp_lg_u32 s33, -1
	s_cselect_b32 s2, s33, 0
	s_cselect_b32 s16, s1, 0
	v_mov_b32_e32 v0, s2
	v_mov_b32_e32 v1, s16
	s_waitcnt lgkmcnt(0)
	s_barrier
	flat_load_dword v0, v[0:1] sc0 sc1
	s_waitcnt vmcnt(0)
	s_mov_b64 s[18:19], -1
	s_waitcnt lgkmcnt(0)
	v_cmp_lt_i32_e32 vcc, v0, v153
	s_and_saveexec_b64 s[16:17], vcc
	s_cbranch_execz .LBB0_1268
	s_mov_b64 s[18:19], 0
	v_mbcnt_lo_u32_b32 v1, -1, 0
	v_mbcnt_hi_u32_b32 v1, -1, v1
	v_lshl_add_u32 v1, v1, 2, s25
	ds_read_b32 v1, v1
	s_waitcnt lgkmcnt(0)
	v_cmp_le_i32_e32 vcc, v1, v0
	s_bcnt1_i32_b64 s2, vcc
	v_mov_b32_e32 v96, s2
	s_or_b64 exec, exec, s[18:19]
	v_lshl_add_u32 v6, v96, 2, 0
	v_add_u32_e32 v6, 0x10000, v6
	ds_read2_b32 v[6:7], v6 offset1:1
	v_lshl_add_u32 v10, v96, 2, 0
	v_add_u32_e32 v1, 0x10120, v10
	ds_read_b32 v1, v1
	v_lshlrev_b32_e32 v2, 15, v96
	v_mov_b32_e32 v3, v97
	v_lshl_add_u64 v[2:3], v[2:3], 2, s[68:69]
	v_lshlrev_b64 v[4:5], 20, v[96:97]
	s_waitcnt lgkmcnt(0)
	v_sub_u32_e32 v6, v7, v6
	v_sub_u32_e32 v0, v0, v1
	v_lshlrev_b32_e32 v122, 7, v0
	v_ashrrev_i32_e32 v123, 31, v122
	v_lshl_add_u64 v[0:1], v[122:123], 2, v[2:3]
	v_mov_b32_e32 v56, 0
	s_mov_b32 s2, 0
	s_mov_b32 s27, 0
	v_mov_b32_e32 v57, v56
	v_mov_b32_e32 v58, v56
	v_mov_b32_e32 v59, v56
	v_mov_b32_e32 v48, v56
	v_mov_b32_e32 v49, v56
	v_mov_b32_e32 v50, v56
	v_mov_b32_e32 v51, v56
	v_mov_b32_e32 v60, v56
	v_mov_b32_e32 v61, v56
	v_mov_b32_e32 v62, v56
	v_mov_b32_e32 v63, v56
	v_mov_b32_e32 v52, v56
	v_mov_b32_e32 v53, v56
	v_mov_b32_e32 v54, v56
	v_mov_b32_e32 v55, v56
	v_mov_b32_e32 v40, v56
	v_mov_b32_e32 v41, v56
	v_mov_b32_e32 v42, v56
	v_mov_b32_e32 v43, v56
	v_mov_b32_e32 v32, v56
	v_mov_b32_e32 v33, v56
	v_mov_b32_e32 v34, v56
	v_mov_b32_e32 v35, v56
	v_mov_b32_e32 v44, v56
	v_mov_b32_e32 v45, v56
	v_mov_b32_e32 v46, v56
	v_mov_b32_e32 v47, v56
	v_mov_b32_e32 v36, v56
	v_mov_b32_e32 v37, v56
	v_mov_b32_e32 v38, v56
	v_mov_b32_e32 v39, v56
	v_mov_b32_e32 v24, v56
	v_mov_b32_e32 v25, v56
	v_mov_b32_e32 v26, v56
	v_mov_b32_e32 v27, v56
	v_mov_b32_e32 v16, v56
	v_mov_b32_e32 v17, v56
	v_mov_b32_e32 v18, v56
	v_mov_b32_e32 v19, v56
	v_mov_b32_e32 v28, v56
	v_mov_b32_e32 v29, v56
	v_mov_b32_e32 v30, v56
	v_mov_b32_e32 v31, v56
	v_mov_b32_e32 v20, v56
	v_mov_b32_e32 v21, v56
	v_mov_b32_e32 v22, v56
	v_mov_b32_e32 v23, v56
	s_waitcnt vmcnt(0)
	v_sub_u32_e32 v2, v6, v122
	v_min_i32_e32 v123, 0x80, v2
	v_cmp_lt_i32_e32 vcc, v160, v123
	s_nop 1
	v_cndmask_b32_e32 v2, 0, v160, vcc
	v_cmp_lt_i32_e32 vcc, v150, v123
	v_lshlrev_b32_e32 v96, 2, v2
	v_lshl_add_u64 v[2:3], v[0:1], 0, v[96:97]
	v_cndmask_b32_e32 v6, 0, v150, vcc
	v_cmp_lt_i32_e32 vcc, v151, v123
	v_lshlrev_b32_e32 v96, 2, v6
	v_lshl_add_u64 v[6:7], v[0:1], 0, v[96:97]
	v_cndmask_b32_e32 v8, 0, v151, vcc
	v_cmp_lt_i32_e32 vcc, v152, v123
	v_lshlrev_b32_e32 v96, 2, v8
	v_lshl_add_u64 v[8:9], v[0:1], 0, v[96:97]
	v_cndmask_b32_e32 v11, 0, v152, vcc
	v_lshlrev_b32_e32 v96, 2, v11
	global_load_dword v2, v[2:3], off
	v_lshl_add_u64 v[0:1], v[0:1], 0, v[96:97]
	global_load_dword v6, v[6:7], off
	v_add_u32_e32 v96, 0x10000, v10
	global_load_dword v8, v[8:9], off
	v_lshl_add_u64 v[10:11], s[74:75], 0, v[4:5]
	global_load_dword v0, v[0:1], off
	v_lshl_add_u64 v[4:5], s[76:77], 0, v[4:5]
	v_cndmask_b32_e64 v133, v5, v11, s[6:7]
	v_cndmask_b32_e64 v132, v4, v10, s[6:7]
	v_cndmask_b32_e64 v135, v11, v5, s[6:7]
	v_cndmask_b32_e64 v134, v10, v4, s[6:7]
	v_cndmask_b32_e64 v137, v5, v11, s[8:9]
	v_cndmask_b32_e64 v136, v4, v10, s[8:9]
	v_lshl_add_u64 v[4:5], v[132:133], 0, v[112:113]
	v_lshl_add_u64 v[10:11], v[134:135], 0, v[114:115]
	v_lshl_add_u64 v[12:13], v[132:133], 0, v[116:117]
	v_lshl_add_u64 v[14:15], v[136:137], 0, v[118:119]
	v_lshl_add_u64 v[4:5], v[4:5], 0, v[124:125]
	v_lshl_add_u64 v[10:11], v[10:11], 0, v[124:125]
	v_lshl_add_u64 v[12:13], v[12:13], 0, v[124:125]
	v_lshl_add_u64 v[14:15], v[14:15], 0, v[124:125]
	global_load_dwordx4 v[64:67], v[4:5], off
	global_load_dwordx4 v[68:71], v[10:11], off
	global_load_dwordx4 v[72:75], v[12:13], off
	global_load_dwordx4 v[80:83], v[14:15], off
	v_lshl_add_u64 v[138:139], v[132:133], 0, s[4:5]
	v_lshl_add_u64 v[134:135], v[134:135], 0, v[106:107]
	v_lshl_add_u64 v[176:177], v[136:137], 0, v[110:111]
	v_mov_b32_e32 v10, v56
	v_mov_b32_e32 v11, v56
	v_mov_b32_e32 v12, v56
	v_mov_b32_e32 v13, v56
	v_mov_b32_e32 v14, v56
	v_mov_b32_e32 v15, v56
	v_lshl_add_u64 v[132:133], v[138:139], 0, v[104:105]
	v_lshl_add_u64 v[134:135], v[134:135], 0, s[4:5]
	v_lshl_add_u64 v[136:137], v[138:139], 0, v[108:109]
	v_lshl_add_u64 v[138:139], v[176:177], 0, s[4:5]
	s_waitcnt vmcnt(7)
	v_ashrrev_i32_e32 v3, 31, v2
	v_lshlrev_b64 v[140:141], 11, v[2:3]
	s_waitcnt vmcnt(6)
	v_ashrrev_i32_e32 v7, 31, v6
	v_lshl_add_u64 v[2:3], v[100:101], 0, v[140:141]
	s_waitcnt vmcnt(5)
	v_ashrrev_i32_e32 v9, 31, v8
	v_lshlrev_b64 v[144:145], 11, v[8:9]
	s_waitcnt vmcnt(4)
	v_ashrrev_i32_e32 v1, 31, v0
	v_lshlrev_b64 v[142:143], 11, v[6:7]
	v_lshl_add_u64 v[6:7], v[100:101], 0, v[144:145]
	v_lshlrev_b64 v[146:147], 11, v[0:1]
	v_lshl_add_u64 v[4:5], v[100:101], 0, v[142:143]
	global_load_dwordx4 v[76:79], v[2:3], off
	global_load_dwordx4 v[84:87], v[4:5], off
	v_lshl_add_u64 v[0:1], v[100:101], 0, v[146:147]
	global_load_dwordx4 v[88:91], v[6:7], off
	global_load_dwordx4 v[92:95], v[0:1], off
	ds_read_b32 v96, v96
	v_mov_b32_e32 v8, v56
	v_mov_b32_e32 v9, v56
	v_mov_b32_e32 v0, v56
	v_mov_b32_e32 v1, v56
	v_mov_b32_e32 v2, v56
	v_mov_b32_e32 v3, v56
	v_mov_b32_e32 v4, v56
	v_mov_b32_e32 v5, v56
	v_mov_b32_e32 v6, v56
	v_lshl_add_u64 v[140:141], s[10:11], 0, v[140:141]
	v_lshl_add_u64 v[142:143], s[10:11], 0, v[142:143]
	v_lshl_add_u64 v[144:145], s[10:11], 0, v[144:145]
	v_lshl_add_u64 v[146:147], s[10:11], 0, v[146:147]
	v_mov_b32_e32 v7, v56
	s_waitcnt vmcnt(7)
	ds_write_b128 v169, v[64:67] offset:16384
	s_waitcnt vmcnt(6)
	ds_write_b128 v169, v[68:71] offset:20480
	s_waitcnt vmcnt(5)
	ds_write_b128 v169, v[72:75] offset:24576
	s_waitcnt vmcnt(4)
	ds_write_b128 v169, v[80:83] offset:28672
	s_waitcnt vmcnt(3)
	ds_write_b128 v169, v[76:79]
	s_waitcnt vmcnt(2)
	ds_write_b128 v169, v[84:87] offset:4096
	s_waitcnt vmcnt(1)
	ds_write_b128 v169, v[88:91] offset:8192
	s_waitcnt vmcnt(0)
	ds_write_b128 v169, v[92:95] offset:12288
	s_waitcnt lgkmcnt(0)
	s_barrier
	s_branch .LBB0_1278

; __device__ void phaseE2(const Params& p, char* smem) {
;     ...
;   xcd_queue_run(p.bar + QW_BASE + 1536, s_rb[NEXP], smem + 2 * GEMM_SMEM + 800, [&](int j, int q) {
;     const int rbg = q, nt = j;
;     int e = 0;
;     while (s_rb[e + 1] <= rbg) e++;
;     const int rb = rbg - s_rb[e];
;     const int cnt = p.cnt[e];
;     const int rows = min(128, cnt - rb * 128);
;     const int slot0 = s_off[e] + rb * 128;
;     const int n0 = nt * 128;
;     const float* wd = p.w_down + (size_t)e * DEXP * DM;
;     const float* lg = p.list_gate + e * CAP + rb * 128;
;     auto rowf = [&](int r) { int rr = r < rows ? r : 0; return (const void*)(p.H + (size_t)(slot0 + rr) * DEXP); };
;     auto colf = [&](int c) { return (const void*)(wd + n0 + c); };
.LBB0_1355:
	s_or_b64 exec, exec, s[16:17]
	s_cmp_lg_u32 s33, -1
	s_cselect_b32 s2, s33, 0
	s_cselect_b32 s16, s1, 0
	v_mov_b32_e32 v0, s2
	v_mov_b32_e32 v1, s16
	s_waitcnt lgkmcnt(0)
	s_barrier
	flat_load_dword v2, v[0:1] sc0 sc1
	s_waitcnt vmcnt(0)
	s_mov_b64 s[18:19], -1
	s_waitcnt lgkmcnt(0)
	v_cmp_lt_i32_e32 vcc, v2, v108
	s_and_saveexec_b64 s[16:17], vcc
	s_cbranch_execz .LBB0_1350
	s_mov_b64 s[18:19], 0
	v_mbcnt_lo_u32_b32 v3, -1, 0
	v_mbcnt_hi_u32_b32 v3, -1, v3
	v_lshl_add_u32 v3, v3, 2, s24
	ds_read_b32 v3, v3
	s_waitcnt lgkmcnt(0)
	v_cmp_le_i32_e32 vcc, v3, v2
	s_bcnt1_i32_b64 s2, vcc
	v_mov_b32_e32 v80, s2
	s_lshl_b32 s20, s2, 21
	s_mov_b32 s21, 0
	v_lshl_add_u64 v[96:97], v[90:91], 0, s[20:21]
	s_or_b64 exec, exec, s[18:19]
	v_mul_u32_u24_e32 v0, 0x20100, v80
	v_mov_b32_e32 v1, 0
	v_lshl_add_u64 v[0:1], v[0:1], 0, s[62:63]
	global_load_dword v3, v[0:1], off
	v_lshl_add_u32 v4, v80, 2, 0
	v_lshlrev_b64 v[0:1], 21, v[80:81]
	v_add_u32_e32 v5, 0x10120, v4
	v_add_u32_e32 v4, 0x10000, v4
	v_lshl_add_u64 v[0:1], v[92:93], 0, v[0:1]
	ds_read_b32 v22, v5
	ds_read_b32 v23, v4
	v_add_co_u32_e32 v4, vcc, s26, v0
	v_mov_b32_e32 v64, 0
	s_nop 0
	v_addc_co_u32_e32 v5, vcc, 0, v1, vcc
	v_add_co_u32_e32 v6, vcc, s27, v0
	s_waitcnt lgkmcnt(1)
	v_sub_u32_e32 v2, v2, v22
	v_addc_co_u32_e32 v7, vcc, 0, v1, vcc
	v_add_co_u32_e32 v8, vcc, s28, v0
	v_lshlrev_b32_e32 v98, 7, v2
	s_nop 0
	v_addc_co_u32_e32 v9, vcc, 0, v1, vcc
	v_add_co_u32_e32 v10, vcc, s29, v0
	s_waitcnt lgkmcnt(0)
	v_add_u32_e32 v117, v23, v98
	v_addc_co_u32_e32 v11, vcc, 0, v1, vcc
	v_add_co_u32_e32 v12, vcc, s30, v0
	s_mov_b32 s2, 0
	s_nop 0
	v_addc_co_u32_e32 v13, vcc, 0, v1, vcc
	v_add_co_u32_e32 v14, vcc, s31, v0
	s_mov_b32 s47, 0
	s_nop 0
	v_addc_co_u32_e32 v15, vcc, 0, v1, vcc
	v_add_co_u32_e32 v16, vcc, s36, v0
	v_mov_b32_e32 v65, v64
	s_nop 0
	v_addc_co_u32_e32 v17, vcc, 0, v1, vcc
	v_add_co_u32_e32 v18, vcc, s25, v0
	global_load_dword v141, v[0:1], off
	global_load_dword v99, v[4:5], off offset:-4096
	global_load_dword v119, v[4:5], off
	global_load_dword v120, v[6:7], off offset:-4096
	global_load_dword v121, v[6:7], off
	global_load_dword v122, v[8:9], off offset:-4096
	global_load_dword v123, v[8:9], off
	global_load_dword v128, v[10:11], off offset:-4096
	global_load_dword v130, v[10:11], off
	global_load_dword v132, v[12:13], off offset:-4096
	global_load_dword v133, v[12:13], off
	global_load_dword v134, v[14:15], off offset:-4096
	global_load_dword v135, v[14:15], off
	global_load_dword v136, v[16:17], off offset:-4096
	global_load_dword v137, v[16:17], off
	v_addc_co_u32_e32 v19, vcc, 0, v1, vcc
	v_add_co_u32_e32 v20, vcc, s37, v0
	v_mov_b32_e32 v66, v64
	s_nop 0
	v_addc_co_u32_e32 v21, vcc, 0, v1, vcc
	v_mov_b32_e32 v67, v64
	v_mov_b32_e32 v76, v64
	v_mov_b32_e32 v77, v64
	v_mov_b32_e32 v78, v64
	v_mov_b32_e32 v79, v64
	v_mov_b32_e32 v72, v64
	v_mov_b32_e32 v73, v64
	v_mov_b32_e32 v74, v64
	v_mov_b32_e32 v75, v64
	v_mov_b32_e32 v68, v64
	v_mov_b32_e32 v69, v64
	v_mov_b32_e32 v70, v64
	v_mov_b32_e32 v71, v64
	v_mov_b32_e32 v60, v64
	v_mov_b32_e32 v61, v64
	v_mov_b32_e32 v62, v64
	v_mov_b32_e32 v63, v64
	v_mov_b32_e32 v56, v64
	v_mov_b32_e32 v57, v64
	v_mov_b32_e32 v58, v64
	v_mov_b32_e32 v59, v64
	v_mov_b32_e32 v52, v64
	v_mov_b32_e32 v53, v64
	v_mov_b32_e32 v54, v64
	v_mov_b32_e32 v55, v64
	v_mov_b32_e32 v48, v64
	v_mov_b32_e32 v49, v64
	v_mov_b32_e32 v50, v64
	s_waitcnt vmcnt(15)
; template <bool ABF, bool BBF, class RowF, class ColF, class Epi>
; __device__ __forceinline__ void gemm_tile(char* smem, int K, RowF rowptr, ColF colptr, int ldb, Epi epi) {
;     ...
;   const int bc = tid & 127, kh = tid >> 7;
;   const float* bp = BBF ? nullptr : ((const float*)colptr(bc) + (size_t)(kh * 32) * ldb);
;   const int br0 = tid >> 3, bcc = (tid & 7) * 8;
;   const char* bq[4];
;   if (BBF) {
; #pragma unroll
;     for (int i = 0; i < 4; i++) bq[i] = (const char*)colptr(br0 + 32 * i) + bcc * 2;
;   }
;   u32x4 ra[NA];
;   float rb[BBF ? 1 : 32];
;   u32x4 rbb[BBF ? 4 : 1];
;   auto gload = [&](int k0) {
; #pragma unroll
;     for (int i = 0; i < NA; i++) ra[i] = *(const u32x4*)(ap[i] + (size_t)k0 * (ABF ? 2 : 4));
;     if (BBF) {
; #pragma unroll
;       for (int i = 0; i < 4; i++) rbb[BBF ? i : 0] = *(const u32x4*)(bq[i] + (size_t)k0 * 2);
;     } else {
;       const float* b = bp + (size_t)k0 * ldb;
; #pragma unroll
;       for (int j = 0; j < 32; j++) rb[BBF ? 0 : j] = b[(size_t)j * ldb];
;     }
;   };
;   auto sstore = [&](int buf) {
;     u16* As = As0 + buf * (GEMM_SMEM / 2);
;     u16* Bs = As + BM * LDT;
; #pragma unroll
;     for (int i = 0; i < NA; i++) {
;       if (ABF) {
;         { const int row = ar0 + ARS * i; *(u32x4*)&As[row * LDT + (((ac >> 3) ^ ((row >> 1) & 7)) << 3)] = ra[i]; }
;       } else {
;         u32x2 v;
;         v[0] = pack2(__uint_as_float(ra[i][0]), __uint_as_float(ra[i][1]));
;         v[1] = pack2(__uint_as_float(ra[i][2]), __uint_as_float(ra[i][3]));
;         { const int row = ar0 + ARS * i; *(u32x2*)&As[row * LDT + (((ac >> 3) ^ ((row >> 1) & 7)) << 3) + (ac & 4)] = v; }
;       }
;     }
;     if (BBF) {
; #pragma unroll
;       for (int i = 0; i < 4; i++) { const int row = br0 + 32 * i; *(u32x4*)&Bs[row * LDT + (((bcc >> 3) ^ ((row >> 1) & 7)) << 3)] = rbb[BBF ? i : 0]; }
;     } else {
; #pragma unroll
;       for (int j = 0; j < 4; j++) {
;         u32x4 v;
;         v[0] = pack2(rb[BBF ? 0 : 8 * j + 0], rb[BBF ? 0 : 8 * j + 1]);
;         v[1] = pack2(rb[BBF ? 0 : 8 * j + 2], rb[BBF ? 0 : 8 * j + 3]);
;         v[2] = pack2(rb[BBF ? 0 : 8 * j + 4], rb[BBF ? 0 : 8 * j + 5]);
;         v[3] = pack2(rb[BBF ? 0 : 8 * j + 6], rb[BBF ? 0 : 8 * j + 7]);
;         *(u32x4*)&Bs[bc * LDT + (((kh * 4 + j) ^ ((bc >> 1) & 7)) << 3)] = v;
;       }
;     }
;   };
;   gload(0);
;   sstore(0);
;   __syncthreads();
	v_sub_u32_e32 v2, v3, v98
	v_min_i32_e32 v118, 0x80, v2
	v_cmp_lt_i32_e32 vcc, v160, v118
	v_mov_b32_e32 v51, v64
	v_mov_b32_e32 v28, v64
	v_cndmask_b32_e32 v2, 0, v160, vcc
	v_cmp_lt_i32_e32 vcc, v150, v118
	v_add_u32_e32 v2, v2, v117
	v_mov_b32_e32 v29, v64
	v_cndmask_b32_e32 v3, 0, v150, vcc
	v_cmp_lt_i32_e32 vcc, v151, v118
	v_add_u32_e32 v4, v3, v117
	v_ashrrev_i32_e32 v3, 31, v2
	v_cndmask_b32_e32 v5, 0, v151, vcc
	v_cmp_lt_i32_e32 vcc, v152, v118
	v_add_u32_e32 v6, v5, v117
	v_ashrrev_i32_e32 v5, 31, v4
	v_cndmask_b32_e32 v7, 0, v152, vcc
	v_add_co_u32_e32 v10, vcc, s38, v0
	v_add_u32_e32 v8, v7, v117
	s_nop 0
	v_addc_co_u32_e32 v11, vcc, 0, v1, vcc
	v_add_co_u32_e32 v12, vcc, s39, v0
	v_ashrrev_i32_e32 v7, 31, v6
	s_nop 0
	v_addc_co_u32_e32 v13, vcc, 0, v1, vcc
	global_load_dword v138, v[18:19], off offset:-4096
	global_load_dword v139, v[18:19], off
	global_load_dword v140, v[20:21], off offset:-4096
	global_load_dword v142, v[20:21], off
	global_load_dword v143, v[10:11], off offset:-4096
	global_load_dword v144, v[10:11], off
	global_load_dword v145, v[12:13], off offset:-4096
	global_load_dword v146, v[12:13], off
	v_add_co_u32_e32 v10, vcc, s40, v0
	v_lshlrev_b64 v[16:17], 10, v[2:3]
	s_nop 0
	v_addc_co_u32_e32 v11, vcc, 0, v1, vcc
	v_add_co_u32_e32 v12, vcc, s41, v0
	v_ashrrev_i32_e32 v9, 31, v8
	s_nop 0
	v_addc_co_u32_e32 v13, vcc, 0, v1, vcc
	v_add_co_u32_e32 v14, vcc, s42, v0
	v_lshlrev_b64 v[22:23], 10, v[4:5]
	s_nop 0
	v_addc_co_u32_e32 v15, vcc, 0, v1, vcc
	v_add_co_u32_e32 v18, vcc, s43, v0
	v_lshlrev_b64 v[24:25], 10, v[6:7]
	s_nop 0
	v_addc_co_u32_e32 v19, vcc, 0, v1, vcc
	v_add_co_u32_e32 v0, vcc, s44, v0
	v_lshl_add_u64 v[2:3], v[86:87], 0, v[16:17]
	s_nop 0
	v_addc_co_u32_e32 v1, vcc, 0, v1, vcc
	global_load_dword v147, v[10:11], off offset:-4096
	global_load_dword v153, v[10:11], off
	global_load_dword v154, v[12:13], off offset:-4096
	global_load_dword v155, v[12:13], off
	global_load_dword v156, v[14:15], off offset:-4096
	global_load_dword v157, v[14:15], off
	global_load_dword v158, v[18:19], off offset:-4096
	global_load_dword v159, v[18:19], off
	global_load_dword v170, v[0:1], off
	v_lshlrev_b64 v[18:19], 10, v[8:9]
	v_lshl_add_u64 v[4:5], v[86:87], 0, v[22:23]
	v_lshl_add_u64 v[6:7], v[86:87], 0, v[24:25]
	v_lshl_add_u64 v[0:1], v[86:87], 0, v[18:19]
	global_load_dwordx4 v[32:35], v[2:3], off
	global_load_dwordx4 v[36:39], v[4:5], off
	global_load_dwordx4 v[40:43], v[6:7], off
	global_load_dwordx4 v[44:47], v[0:1], off
	s_waitcnt vmcnt(34)
	v_cvt_pk_bf16_f32 v0, v141, v99
	s_waitcnt vmcnt(32)
	v_cvt_pk_bf16_f32 v1, v119, v120
	s_waitcnt vmcnt(30)
	v_cvt_pk_bf16_f32 v2, v121, v122
	s_waitcnt vmcnt(28)
	v_cvt_pk_bf16_f32 v3, v123, v128
	s_waitcnt vmcnt(26)
	v_cvt_pk_bf16_f32 v4, v130, v132
	s_waitcnt vmcnt(24)
	v_cvt_pk_bf16_f32 v5, v133, v134
	s_waitcnt vmcnt(22)
	v_cvt_pk_bf16_f32 v6, v135, v136
	v_lshl_add_u64 v[100:101], s[8:9], 0, v[16:17]
	v_lshl_add_u64 v[102:103], s[8:9], 0, v[22:23]
	v_lshl_add_u64 v[104:105], s[8:9], 0, v[24:25]
	v_lshl_add_u64 v[106:107], s[8:9], 0, v[18:19]
	v_mov_b32_e32 v30, v64
	v_mov_b32_e32 v31, v64
	v_mov_b32_e32 v24, v64
	v_mov_b32_e32 v25, v64
	v_mov_b32_e32 v26, v64
	v_mov_b32_e32 v27, v64
	v_mov_b32_e32 v20, v64
	v_mov_b32_e32 v21, v64
	v_mov_b32_e32 v22, v64
	v_mov_b32_e32 v23, v64
	v_mov_b32_e32 v16, v64
	v_mov_b32_e32 v17, v64
	v_mov_b32_e32 v18, v64
	v_mov_b32_e32 v19, v64
	s_waitcnt vmcnt(20)
	v_cvt_pk_bf16_f32 v7, v137, v138
	s_waitcnt vmcnt(18)
	v_cvt_pk_bf16_f32 v8, v139, v140
	s_waitcnt vmcnt(16)
	v_cvt_pk_bf16_f32 v9, v142, v143
	s_waitcnt vmcnt(14)
	v_cvt_pk_bf16_f32 v10, v144, v145
	s_waitcnt vmcnt(12)
	v_cvt_pk_bf16_f32 v11, v146, v147
	s_waitcnt vmcnt(10)
	v_cvt_pk_bf16_f32 v12, v153, v154
	s_waitcnt vmcnt(8)
	v_cvt_pk_bf16_f32 v13, v155, v156
	s_waitcnt vmcnt(6)
	v_cvt_pk_bf16_f32 v14, v157, v158
	s_waitcnt vmcnt(4)
	v_cvt_pk_bf16_f32 v15, v159, v170
	s_waitcnt vmcnt(3)
	ds_write_b128 v169, v[32:35]
	s_waitcnt vmcnt(2)
	ds_write_b128 v169, v[36:39] offset:4096
	s_waitcnt vmcnt(1)
	ds_write_b128 v169, v[40:43] offset:8192
	s_waitcnt vmcnt(0)
	ds_write_b128 v169, v[44:47] offset:12288
	ds_write_b128 v113, v[0:3] offset:16384
	ds_write_b128 v114, v[4:7] offset:16384
	ds_write_b128 v115, v[8:11] offset:16384
	ds_write_b128 v116, v[12:15] offset:16384
	v_mov_b32_e32 v12, v64
	v_mov_b32_e32 v13, v64
	v_mov_b32_e32 v14, v64
	v_mov_b32_e32 v15, v64
	v_mov_b32_e32 v8, v64
	v_mov_b32_e32 v9, v64
	v_mov_b32_e32 v10, v64
	v_mov_b32_e32 v11, v64
	v_mov_b32_e32 v4, v64
	v_mov_b32_e32 v5, v64
	v_mov_b32_e32 v6, v64
	v_mov_b32_e32 v7, v64
	v_mov_b32_e32 v0, v64
	v_mov_b32_e32 v1, v64
	v_mov_b32_e32 v2, v64
	v_mov_b32_e32 v3, v64
	s_waitcnt lgkmcnt(0)
	s_barrier
	s_branch .LBB0_1360
